# norm-GEMM epilogue start: cache-touch of K-tiles 2..5 of the next unit's weight tile (lands during the epilogue)
# baseline (speedup 1.0000x reference)
.LBB0_417:
	s_mov_b32 s62, s3
	s_mov_b32 s63, s23
	v_mbcnt_lo_u32_b32 v210, -1, 0
	v_mbcnt_hi_u32_b32 v210, -1, v210
	v_add_u32_e32 v210, s33, v210
	v_lshrrev_b32_e32 v211, 1, v210
	v_and_b32_e32 v210, 1, v210
	v_lshlrev_b32_e32 v211, 11, v211
	v_lshl_add_u32 v210, v210, 7, v211
	global_load_dword v212, v210, s[62:63] offset:256
	global_load_dword v213, v210, s[62:63] offset:512
	s_and_b64 vcc, exec, s[20:21]
	s_cbranch_vccz .LBB0_419
	s_barrier
